# ssd_out B/C conv halo loads de-serialized as well
# baseline (speedup 1.0000x reference)
.LBB0_558:
	s_lshl_b32 s10, s8, 7
	v_or_b32_e32 v2, s10, v168
	v_lshlrev_b64 v[20:21], 2, v[2:3]
	v_lshl_add_u64 v[4:5], s[54:55], 0, v[20:21]
	v_lshl_add_u64 v[8:9], s[16:17], 0, v[20:21]
	v_lshl_add_u64 v[12:13], s[88:89], 0, v[20:21]
	v_lshl_add_u64 v[16:17], s[90:91], 0, v[20:21]
	v_lshl_add_u64 v[20:21], s[6:7], 0, v[20:21]
	global_load_dwordx4 v[4:7], v[4:5], off
	s_nop 0
	global_load_dwordx4 v[8:11], v[8:9], off
	s_nop 0
	global_load_dwordx4 v[12:15], v[12:13], off
	s_nop 0
	global_load_dwordx4 v[16:19], v[16:17], off
	v_add_u32_e32 v2, s10, v137
	global_load_dwordx4 v[20:23], v[20:21], off
	v_lshl_add_u64 v[26:27], v[2:3], 1, s[96:97]
	s_mov_b64 s[0:1], 0x800
	v_cndmask_b32_e64 v2, 0, 1, s[94:95]
	v_lshl_add_u64 v[24:25], v[26:27], 0, s[0:1]
	v_cmp_ne_u32_e64 s[50:51], 1, v2
	s_andn2_b64 vcc, exec, s[94:95]
	v_mov_b32_e32 v58, 0
	s_cbranch_vccnz .LBB0_587
	v_add_co_u32_e32 v28, vcc, 0xffffc000, v24
	s_nop 1
	v_addc_co_u32_e32 v29, vcc, -1, v25, vcc
	global_load_dwordx2 v[30:31], v[28:29], off
	v_add_co_u32_e32 v28, vcc, 0xffffe000, v24
	s_nop 1
	v_addc_co_u32_e32 v29, vcc, -1, v25, vcc
	global_load_dwordx2 v[28:29], v[28:29], off offset:-1536
	s_and_b64 vcc, exec, s[50:51]
	v_mov_b32_e32 v59, 0
	s_cbranch_vccnz .LBB0_561

.LBB0_561:
	global_load_dwordx2 v[64:65], v[24:25], off offset:3584
	v_add_co_u32_e32 v26, vcc, 0x2000, v24
	s_nop 1
	v_addc_co_u32_e32 v27, vcc, 0, v25, vcc
	global_load_dwordx2 v[54:55], v[26:27], off offset:2048
	v_add_co_u32_e32 v26, vcc, 0x4000, v24
	s_nop 1
	v_addc_co_u32_e32 v27, vcc, 0, v25, vcc
	global_load_dwordx2 v[50:51], v[26:27], off offset:512
	v_add_co_u32_e32 v26, vcc, 0x5000, v24
	s_nop 1
	v_addc_co_u32_e32 v27, vcc, 0, v25, vcc
	global_load_dwordx2 v[48:49], v[26:27], off offset:3072
	v_add_co_u32_e32 v26, vcc, 0x7000, v24
	s_nop 1
	v_addc_co_u32_e32 v27, vcc, 0, v25, vcc
	global_load_dwordx2 v[46:47], v[26:27], off offset:1536
	v_add_co_u32_e32 v26, vcc, 0x9000, v24
	s_nop 1
	v_addc_co_u32_e32 v27, vcc, 0, v25, vcc
	global_load_dwordx2 v[44:45], v[26:27], off
	v_add_co_u32_e32 v26, vcc, s35, v24
	s_mov_b32 s10, s63
	s_nop 0
	v_addc_co_u32_e32 v27, vcc, 0, v25, vcc
	global_load_dwordx2 v[42:43], v[26:27], off offset:2560
	v_add_co_u32_e32 v26, vcc, s36, v24
	s_waitcnt vmcnt(6)
	v_lshlrev_b32_e32 v66, 16, v30
	v_and_b32_e32 v67, 0xffff0000, v30
	v_lshlrev_b32_e32 v62, 16, v31
	v_and_b32_e32 v63, 0xffff0000, v31
	v_lshlrev_b32_e32 v68, 16, v58
	v_and_b32_e32 v69, 0xffff0000, v58
	v_lshlrev_b32_e32 v56, 16, v28
	v_and_b32_e32 v57, 0xffff0000, v28
	v_lshlrev_b32_e32 v52, 16, v29
	v_and_b32_e32 v53, 0xffff0000, v29
	v_lshlrev_b32_e32 v60, 16, v64
	v_and_b32_e32 v61, 0xffff0000, v64
	v_pk_fma_f32 v[70:71], v[60:61], v[16:17], v[20:21]
	v_lshlrev_b32_e32 v58, 16, v65
	v_pk_fma_f32 v[70:71], v[68:69], v[12:13], v[70:71]
	v_addc_co_u32_e32 v27, vcc, 0, v25, vcc
	v_pk_fma_f32 v[70:71], v[56:57], v[8:9], v[70:71]
	global_load_dwordx2 v[40:41], v[26:27], off offset:1024
	v_pk_fma_f32 v[66:67], v[66:67], v[4:5], v[70:71]
	v_add_co_u32_e32 v26, vcc, 0xd000, v24
	v_mul_f32_e32 v2, 0xbfb8aa3b, v66
	v_exp_f32_e32 v2, v2
	v_addc_co_u32_e32 v27, vcc, 0, v25, vcc
	global_load_dwordx2 v[38:39], v[26:27], off offset:3584
	v_add_f32_e32 v2, 1.0, v2
	v_rcp_f32_e32 v70, v2
	v_mul_f32_e32 v2, 0xbfb8aa3b, v67
	v_exp_f32_e32 v2, v2
	v_add_co_u32_e32 v26, vcc, 0xf000, v24
	v_add_f32_e32 v2, 1.0, v2
	v_rcp_f32_e32 v71, v2
	v_addc_co_u32_e32 v27, vcc, 0, v25, vcc
	global_load_dwordx2 v[36:37], v[26:27], off offset:2048
	v_pk_mul_f32 v[66:67], v[66:67], v[70:71]
	v_lshlrev_b32_e32 v70, 16, v59
	v_and_b32_e32 v71, 0xffff0000, v59
	v_and_b32_e32 v59, 0xffff0000, v65
	v_cvt_pk_bf16_f32 v64, v66, v67
	v_pk_fma_f32 v[66:67], v[58:59], v[18:19], v[22:23]
	v_add_co_u32_e32 v26, vcc, s56, v24
	v_pk_fma_f32 v[66:67], v[70:71], v[14:15], v[66:67]
	s_nop 0
	v_addc_co_u32_e32 v27, vcc, 0, v25, vcc
	v_pk_fma_f32 v[66:67], v[52:53], v[10:11], v[66:67]
	global_load_dwordx2 v[34:35], v[26:27], off offset:512
	v_pk_fma_f32 v[62:63], v[62:63], v[6:7], v[66:67]
	v_add_co_u32_e32 v26, vcc, s33, v24
	v_mul_f32_e32 v2, 0xbfb8aa3b, v62
	v_exp_f32_e32 v2, v2
	v_addc_co_u32_e32 v27, vcc, 0, v25, vcc
	global_load_dwordx2 v[32:33], v[26:27], off offset:3072
	v_add_f32_e32 v2, 1.0, v2
	v_rcp_f32_e32 v66, v2
	v_mul_f32_e32 v2, 0xbfb8aa3b, v63
	v_exp_f32_e32 v2, v2
	v_add_co_u32_e32 v26, vcc, s65, v24
	v_add_f32_e32 v2, 1.0, v2
	v_rcp_f32_e32 v67, v2
	v_addc_co_u32_e32 v27, vcc, 0, v25, vcc
	global_load_dwordx2 v[30:31], v[26:27], off offset:1536
	v_pk_mul_f32 v[62:63], v[62:63], v[66:67]
	v_add_co_u32_e32 v26, vcc, s31, v24
	v_cvt_pk_bf16_f32 v65, v62, v63
	s_waitcnt vmcnt(11)
	v_lshlrev_b32_e32 v62, 16, v54
	v_and_b32_e32 v63, 0xffff0000, v54
	v_pk_fma_f32 v[66:67], v[62:63], v[16:17], v[20:21]
	v_lshlrev_b32_e32 v54, 16, v55
	v_pk_fma_f32 v[66:67], v[60:61], v[12:13], v[66:67]
	v_and_b32_e32 v55, 0xffff0000, v55
	v_pk_fma_f32 v[66:67], v[68:69], v[8:9], v[66:67]
	v_addc_co_u32_e32 v27, vcc, 0, v25, vcc
	v_pk_fma_f32 v[56:57], v[56:57], v[4:5], v[66:67]
	global_load_dwordx2 v[28:29], v[26:27], off
	v_mul_f32_e32 v2, 0xbfb8aa3b, v56
	v_exp_f32_e32 v2, v2
	v_add_co_u32_e32 v26, vcc, s58, v24
	v_add_f32_e32 v2, 1.0, v2
	v_rcp_f32_e32 v66, v2
	v_mul_f32_e32 v2, 0xbfb8aa3b, v57
	v_exp_f32_e32 v2, v2
	v_addc_co_u32_e32 v27, vcc, 0, v25, vcc
	global_load_dwordx2 v[26:27], v[26:27], off offset:2560
	v_add_f32_e32 v2, 1.0, v2
	v_rcp_f32_e32 v67, v2
	v_add_co_u32_e32 v24, vcc, s59, v24
	v_pk_mul_f32 v[56:57], v[56:57], v[66:67]
	v_pk_fma_f32 v[66:67], v[54:55], v[18:19], v[22:23]
	v_cvt_pk_bf16_f32 v56, v56, v57
	v_pk_fma_f32 v[66:67], v[58:59], v[14:15], v[66:67]
	v_addc_co_u32_e32 v25, vcc, 0, v25, vcc
	v_pk_fma_f32 v[66:67], v[70:71], v[10:11], v[66:67]
	global_load_dwordx2 v[24:25], v[24:25], off offset:1024
	v_pk_fma_f32 v[52:53], v[52:53], v[6:7], v[66:67]
	s_andn2_b64 vcc, exec, s[20:21]
	v_mul_f32_e32 v2, 0xbfb8aa3b, v52
	v_exp_f32_e32 v2, v2
	s_nop 0
	v_add_f32_e32 v2, 1.0, v2
	v_rcp_f32_e32 v66, v2
	v_mul_f32_e32 v2, 0xbfb8aa3b, v53
	v_exp_f32_e32 v2, v2
	s_nop 0
	v_add_f32_e32 v2, 1.0, v2
	v_rcp_f32_e32 v67, v2
	s_nop 0
	v_pk_mul_f32 v[52:53], v[52:53], v[66:67]
	s_waitcnt vmcnt(13)
	v_lshlrev_b32_e32 v66, 16, v50
	v_and_b32_e32 v67, 0xffff0000, v50
	v_cvt_pk_bf16_f32 v57, v52, v53
	v_pk_fma_f32 v[52:53], v[66:67], v[16:17], v[20:21]
	ds_write2_b64 v169, v[64:65], v[56:57] offset1:34
	v_pk_fma_f32 v[52:53], v[62:63], v[12:13], v[52:53]
	v_lshlrev_b32_e32 v64, 16, v51
	v_pk_fma_f32 v[52:53], v[60:61], v[8:9], v[52:53]
	v_and_b32_e32 v65, 0xffff0000, v51
	v_pk_fma_f32 v[52:53], v[68:69], v[4:5], v[52:53]
	v_pk_fma_f32 v[50:51], v[64:65], v[18:19], v[22:23]
	v_mul_f32_e32 v2, 0xbfb8aa3b, v52
	v_exp_f32_e32 v2, v2
	v_pk_fma_f32 v[50:51], v[54:55], v[14:15], v[50:51]
	v_add_f32_e32 v2, 1.0, v2
	v_rcp_f32_e32 v56, v2
	v_mul_f32_e32 v2, 0xbfb8aa3b, v53
	v_exp_f32_e32 v2, v2
	v_pk_fma_f32 v[50:51], v[58:59], v[10:11], v[50:51]
	v_add_f32_e32 v2, 1.0, v2
	v_pk_fma_f32 v[50:51], v[70:71], v[6:7], v[50:51]
	v_rcp_f32_e32 v57, v2
	v_mul_f32_e32 v2, 0xbfb8aa3b, v50
	v_exp_f32_e32 v2, v2
	v_pk_mul_f32 v[52:53], v[52:53], v[56:57]
	s_nop 0
	v_cvt_pk_bf16_f32 v52, v52, v53
	v_add_f32_e32 v2, 1.0, v2
	v_rcp_f32_e32 v56, v2
	v_mul_f32_e32 v2, 0xbfb8aa3b, v51
	v_exp_f32_e32 v2, v2
	s_nop 0
	v_add_f32_e32 v2, 1.0, v2
	v_rcp_f32_e32 v57, v2
	s_nop 0
	v_pk_mul_f32 v[50:51], v[50:51], v[56:57]
	s_nop 0
	v_cvt_pk_bf16_f32 v53, v50, v51
	s_waitcnt vmcnt(12)
	v_lshlrev_b32_e32 v50, 16, v48
	v_and_b32_e32 v51, 0xffff0000, v48
	v_pk_fma_f32 v[56:57], v[50:51], v[16:17], v[20:21]
	v_lshlrev_b32_e32 v48, 16, v49
	v_pk_fma_f32 v[56:57], v[66:67], v[12:13], v[56:57]
	v_and_b32_e32 v49, 0xffff0000, v49
	v_pk_fma_f32 v[56:57], v[62:63], v[8:9], v[56:57]
	s_nop 0
	v_pk_fma_f32 v[56:57], v[60:61], v[4:5], v[56:57]
	s_nop 0
	v_mul_f32_e32 v2, 0xbfb8aa3b, v56
	v_exp_f32_e32 v2, v2
	s_nop 0
	v_add_f32_e32 v2, 1.0, v2
	v_rcp_f32_e32 v60, v2
	v_mul_f32_e32 v2, 0xbfb8aa3b, v57
	v_exp_f32_e32 v2, v2
	s_nop 0
	v_add_f32_e32 v2, 1.0, v2
	v_rcp_f32_e32 v61, v2
	s_nop 0
	v_pk_mul_f32 v[56:57], v[56:57], v[60:61]
	v_pk_fma_f32 v[60:61], v[48:49], v[18:19], v[22:23]
	v_cvt_pk_bf16_f32 v56, v56, v57
	v_pk_fma_f32 v[60:61], v[64:65], v[14:15], v[60:61]
	s_nop 0
	v_pk_fma_f32 v[60:61], v[54:55], v[10:11], v[60:61]
	s_nop 0
	v_pk_fma_f32 v[58:59], v[58:59], v[6:7], v[60:61]
	s_nop 0
	v_mul_f32_e32 v2, 0xbfb8aa3b, v58
	v_exp_f32_e32 v2, v2
	s_nop 0
	v_add_f32_e32 v2, 1.0, v2
	v_rcp_f32_e32 v60, v2
	v_mul_f32_e32 v2, 0xbfb8aa3b, v59
	v_exp_f32_e32 v2, v2
	s_nop 0
	v_add_f32_e32 v2, 1.0, v2
	v_rcp_f32_e32 v61, v2
	s_nop 0
	v_pk_mul_f32 v[58:59], v[58:59], v[60:61]
	s_nop 0
	v_cvt_pk_bf16_f32 v57, v58, v59
	ds_write2_b64 v169, v[52:53], v[56:57] offset0:68 offset1:102
	s_waitcnt vmcnt(11)
	v_lshlrev_b32_e32 v56, 16, v46
	v_and_b32_e32 v57, 0xffff0000, v46
	v_pk_fma_f32 v[52:53], v[56:57], v[16:17], v[20:21]
	s_nop 0
	v_pk_fma_f32 v[52:53], v[50:51], v[12:13], v[52:53]
	s_nop 0
	v_pk_fma_f32 v[52:53], v[66:67], v[8:9], v[52:53]
	s_nop 0
	v_pk_fma_f32 v[52:53], v[62:63], v[4:5], v[52:53]
	s_nop 0
	v_mul_f32_e32 v2, 0xbfb8aa3b, v52
	v_exp_f32_e32 v2, v2
	s_nop 0
	v_add_f32_e32 v2, 1.0, v2
	v_rcp_f32_e32 v58, v2
	v_mul_f32_e32 v2, 0xbfb8aa3b, v53
	v_exp_f32_e32 v2, v2
	s_nop 0
	v_add_f32_e32 v2, 1.0, v2
	v_rcp_f32_e32 v59, v2
	s_nop 0
	v_pk_mul_f32 v[52:53], v[52:53], v[58:59]
	s_nop 0
	v_cvt_pk_bf16_f32 v58, v52, v53
	v_lshlrev_b32_e32 v52, 16, v47
	v_and_b32_e32 v53, 0xffff0000, v47
	v_pk_fma_f32 v[46:47], v[52:53], v[18:19], v[22:23]
	s_nop 0
	v_pk_fma_f32 v[46:47], v[48:49], v[14:15], v[46:47]
	s_nop 0
	v_pk_fma_f32 v[46:47], v[64:65], v[10:11], v[46:47]
	s_nop 0
	v_pk_fma_f32 v[46:47], v[54:55], v[6:7], v[46:47]
	s_nop 0
	v_mul_f32_e32 v2, 0xbfb8aa3b, v46
	v_exp_f32_e32 v2, v2
	s_nop 0
	v_add_f32_e32 v2, 1.0, v2
	v_rcp_f32_e32 v54, v2
	v_mul_f32_e32 v2, 0xbfb8aa3b, v47
	v_exp_f32_e32 v2, v2
	s_nop 0
	v_add_f32_e32 v2, 1.0, v2
	v_rcp_f32_e32 v55, v2
	s_nop 0
	v_pk_mul_f32 v[46:47], v[46:47], v[54:55]
	s_nop 0
	v_cvt_pk_bf16_f32 v59, v46, v47
	s_waitcnt vmcnt(10)
	v_lshlrev_b32_e32 v46, 16, v44
	v_and_b32_e32 v47, 0xffff0000, v44
	v_pk_fma_f32 v[54:55], v[46:47], v[16:17], v[20:21]
	s_nop 0
	v_pk_fma_f32 v[54:55], v[56:57], v[12:13], v[54:55]
	s_nop 0
	v_pk_fma_f32 v[54:55], v[50:51], v[8:9], v[54:55]
	s_nop 0
	v_pk_fma_f32 v[54:55], v[66:67], v[4:5], v[54:55]
	s_nop 0
	v_mul_f32_e32 v2, 0xbfb8aa3b, v54
	v_exp_f32_e32 v2, v2
	s_nop 0
	v_add_f32_e32 v2, 1.0, v2
	v_rcp_f32_e32 v60, v2
	v_mul_f32_e32 v2, 0xbfb8aa3b, v55
	v_exp_f32_e32 v2, v2
	s_nop 0
	v_add_f32_e32 v2, 1.0, v2
	v_rcp_f32_e32 v61, v2
	s_nop 0
	v_pk_mul_f32 v[54:55], v[54:55], v[60:61]
	s_nop 0
	v_cvt_pk_bf16_f32 v44, v54, v55
	v_lshlrev_b32_e32 v54, 16, v45
	v_and_b32_e32 v55, 0xffff0000, v45
	v_pk_fma_f32 v[60:61], v[54:55], v[18:19], v[22:23]
	s_nop 0
	v_pk_fma_f32 v[60:61], v[52:53], v[14:15], v[60:61]
	s_nop 0
	v_pk_fma_f32 v[60:61], v[48:49], v[10:11], v[60:61]
	s_nop 0
	v_pk_fma_f32 v[60:61], v[64:65], v[6:7], v[60:61]
	s_nop 0
	v_mul_f32_e32 v2, 0xbfb8aa3b, v60
	v_exp_f32_e32 v2, v2
	s_nop 0
	v_add_f32_e32 v2, 1.0, v2
	v_rcp_f32_e32 v62, v2
	v_mul_f32_e32 v2, 0xbfb8aa3b, v61
	v_exp_f32_e32 v2, v2
	s_nop 0
	v_add_f32_e32 v2, 1.0, v2
	v_rcp_f32_e32 v63, v2
	s_nop 0
	v_pk_mul_f32 v[60:61], v[60:61], v[62:63]
	s_nop 0
	v_cvt_pk_bf16_f32 v45, v60, v61
	ds_write2_b64 v169, v[58:59], v[44:45] offset0:136 offset1:170
	s_waitcnt vmcnt(9)
	v_lshlrev_b32_e32 v58, 16, v42
	v_and_b32_e32 v59, 0xffff0000, v42
	v_pk_fma_f32 v[44:45], v[58:59], v[16:17], v[20:21]
	s_nop 0
	v_pk_fma_f32 v[44:45], v[46:47], v[12:13], v[44:45]
	s_nop 0
	v_pk_fma_f32 v[44:45], v[56:57], v[8:9], v[44:45]
	s_nop 0
	v_pk_fma_f32 v[44:45], v[50:51], v[4:5], v[44:45]
	s_nop 0
	v_mul_f32_e32 v2, 0xbfb8aa3b, v44
	v_exp_f32_e32 v2, v2
	s_nop 0
	v_add_f32_e32 v2, 1.0, v2
	v_rcp_f32_e32 v50, v2
	v_mul_f32_e32 v2, 0xbfb8aa3b, v45
	v_exp_f32_e32 v2, v2
	s_nop 0
	v_add_f32_e32 v2, 1.0, v2
	v_rcp_f32_e32 v51, v2
	s_nop 0
	v_pk_mul_f32 v[44:45], v[44:45], v[50:51]
	v_lshlrev_b32_e32 v50, 16, v43
	v_and_b32_e32 v51, 0xffff0000, v43
	v_pk_fma_f32 v[42:43], v[50:51], v[18:19], v[22:23]
	v_cvt_pk_bf16_f32 v44, v44, v45
	v_pk_fma_f32 v[42:43], v[54:55], v[14:15], v[42:43]
	s_nop 0
	v_pk_fma_f32 v[42:43], v[52:53], v[10:11], v[42:43]
	s_nop 0
	v_pk_fma_f32 v[42:43], v[48:49], v[6:7], v[42:43]
	s_nop 0
	v_mul_f32_e32 v2, 0xbfb8aa3b, v42
	v_exp_f32_e32 v2, v2
	s_nop 0
	v_add_f32_e32 v2, 1.0, v2
	v_rcp_f32_e32 v48, v2
	v_mul_f32_e32 v2, 0xbfb8aa3b, v43
	v_exp_f32_e32 v2, v2
	s_nop 0
	v_add_f32_e32 v2, 1.0, v2
	v_rcp_f32_e32 v49, v2
	s_nop 0
	v_pk_mul_f32 v[42:43], v[42:43], v[48:49]
	s_nop 0
	v_cvt_pk_bf16_f32 v45, v42, v43
	s_waitcnt vmcnt(8)
	v_lshlrev_b32_e32 v42, 16, v40
	v_and_b32_e32 v43, 0xffff0000, v40
	v_pk_fma_f32 v[48:49], v[42:43], v[16:17], v[20:21]
	v_lshlrev_b32_e32 v40, 16, v41
	v_pk_fma_f32 v[48:49], v[58:59], v[12:13], v[48:49]
	v_and_b32_e32 v41, 0xffff0000, v41
	v_pk_fma_f32 v[48:49], v[46:47], v[8:9], v[48:49]
	s_nop 0
	v_pk_fma_f32 v[48:49], v[56:57], v[4:5], v[48:49]
	s_nop 0
	v_mul_f32_e32 v2, 0xbfb8aa3b, v48
	v_exp_f32_e32 v2, v2
	s_nop 0
	v_add_f32_e32 v2, 1.0, v2
	v_rcp_f32_e32 v56, v2
	v_mul_f32_e32 v2, 0xbfb8aa3b, v49
	v_exp_f32_e32 v2, v2
	s_nop 0
	v_add_f32_e32 v2, 1.0, v2
	v_rcp_f32_e32 v57, v2
	s_nop 0
	v_pk_mul_f32 v[48:49], v[48:49], v[56:57]
	v_pk_fma_f32 v[56:57], v[40:41], v[18:19], v[22:23]
	v_cvt_pk_bf16_f32 v48, v48, v49
	v_pk_fma_f32 v[56:57], v[50:51], v[14:15], v[56:57]
	s_nop 0
	v_pk_fma_f32 v[56:57], v[54:55], v[10:11], v[56:57]
	s_nop 0
	v_pk_fma_f32 v[52:53], v[52:53], v[6:7], v[56:57]
	s_nop 0
	v_mul_f32_e32 v2, 0xbfb8aa3b, v52
	v_exp_f32_e32 v2, v2
	s_nop 0
	v_add_f32_e32 v2, 1.0, v2
	v_rcp_f32_e32 v56, v2
	v_mul_f32_e32 v2, 0xbfb8aa3b, v53
	v_exp_f32_e32 v2, v2
	s_nop 0
	v_add_f32_e32 v2, 1.0, v2
	v_rcp_f32_e32 v57, v2
	s_nop 0
	v_pk_mul_f32 v[52:53], v[52:53], v[56:57]
	s_nop 0
	v_cvt_pk_bf16_f32 v49, v52, v53
	ds_write2_b64 v169, v[44:45], v[48:49] offset0:204 offset1:238
	s_waitcnt vmcnt(7)
	v_lshlrev_b32_e32 v48, 16, v38
	v_and_b32_e32 v49, 0xffff0000, v38
	v_pk_fma_f32 v[44:45], v[48:49], v[16:17], v[20:21]
	s_nop 0
	v_pk_fma_f32 v[44:45], v[42:43], v[12:13], v[44:45]
	s_nop 0
	v_pk_fma_f32 v[44:45], v[58:59], v[8:9], v[44:45]
	s_nop 0
	v_pk_fma_f32 v[44:45], v[46:47], v[4:5], v[44:45]
	s_nop 0
	v_mul_f32_e32 v2, 0xbfb8aa3b, v44
	v_exp_f32_e32 v2, v2
	s_nop 0
	v_add_f32_e32 v2, 1.0, v2
	v_rcp_f32_e32 v46, v2
	v_mul_f32_e32 v2, 0xbfb8aa3b, v45
	v_exp_f32_e32 v2, v2
	s_nop 0
	v_add_f32_e32 v2, 1.0, v2
	v_rcp_f32_e32 v47, v2
	s_nop 0
	v_pk_mul_f32 v[44:45], v[44:45], v[46:47]
	s_nop 0
	v_cvt_pk_bf16_f32 v46, v44, v45
	v_lshlrev_b32_e32 v44, 16, v39
	v_and_b32_e32 v45, 0xffff0000, v39
	v_pk_fma_f32 v[38:39], v[44:45], v[18:19], v[22:23]
	s_nop 0
	v_pk_fma_f32 v[38:39], v[40:41], v[14:15], v[38:39]
	s_nop 0
	v_pk_fma_f32 v[38:39], v[50:51], v[10:11], v[38:39]
	s_nop 0
	v_pk_fma_f32 v[38:39], v[54:55], v[6:7], v[38:39]
	s_nop 0
	v_mul_f32_e32 v2, 0xbfb8aa3b, v38
	v_exp_f32_e32 v2, v2
	s_nop 0
	v_add_f32_e32 v2, 1.0, v2
	v_rcp_f32_e32 v52, v2
	v_mul_f32_e32 v2, 0xbfb8aa3b, v39
	v_exp_f32_e32 v2, v2
	s_nop 0
	v_add_f32_e32 v2, 1.0, v2
	v_rcp_f32_e32 v53, v2
	s_nop 0
	v_pk_mul_f32 v[38:39], v[38:39], v[52:53]
	s_nop 0
	v_cvt_pk_bf16_f32 v47, v38, v39
	s_waitcnt vmcnt(6)
	v_lshlrev_b32_e32 v38, 16, v36
	v_and_b32_e32 v39, 0xffff0000, v36
	v_pk_fma_f32 v[52:53], v[38:39], v[16:17], v[20:21]
	v_lshlrev_b32_e32 v36, 16, v37
	v_pk_fma_f32 v[52:53], v[48:49], v[12:13], v[52:53]
	v_and_b32_e32 v37, 0xffff0000, v37
	v_pk_fma_f32 v[52:53], v[42:43], v[8:9], v[52:53]
	s_nop 0
	v_pk_fma_f32 v[52:53], v[58:59], v[4:5], v[52:53]
	s_nop 0
	v_mul_f32_e32 v2, 0xbfb8aa3b, v52
	v_exp_f32_e32 v2, v2
	s_nop 0
	v_add_f32_e32 v2, 1.0, v2
	v_rcp_f32_e32 v54, v2
	v_mul_f32_e32 v2, 0xbfb8aa3b, v53
	v_exp_f32_e32 v2, v2
	s_nop 0
	v_add_f32_e32 v2, 1.0, v2
	v_rcp_f32_e32 v55, v2
	s_nop 0
	v_pk_mul_f32 v[52:53], v[52:53], v[54:55]
	v_pk_fma_f32 v[54:55], v[36:37], v[18:19], v[22:23]
	v_cvt_pk_bf16_f32 v52, v52, v53
	v_pk_fma_f32 v[54:55], v[44:45], v[14:15], v[54:55]
	s_nop 0
	v_pk_fma_f32 v[54:55], v[40:41], v[10:11], v[54:55]
	s_nop 0
	v_pk_fma_f32 v[50:51], v[50:51], v[6:7], v[54:55]
	s_nop 0
	v_mul_f32_e32 v2, 0xbfb8aa3b, v50
	v_exp_f32_e32 v2, v2
	s_nop 0
	v_add_f32_e32 v2, 1.0, v2
	v_rcp_f32_e32 v54, v2
	v_mul_f32_e32 v2, 0xbfb8aa3b, v51
	v_exp_f32_e32 v2, v2
	s_nop 0
	v_add_f32_e32 v2, 1.0, v2
	v_rcp_f32_e32 v55, v2
	v_add_u32_e32 v2, 0x800, v169
	v_pk_mul_f32 v[50:51], v[50:51], v[54:55]
	s_nop 0
	v_cvt_pk_bf16_f32 v53, v50, v51
	ds_write2_b64 v2, v[46:47], v[52:53] offset0:16 offset1:50
	s_waitcnt vmcnt(5)
	v_lshlrev_b32_e32 v46, 16, v34
	v_and_b32_e32 v47, 0xffff0000, v34
	v_pk_fma_f32 v[50:51], v[46:47], v[16:17], v[20:21]
	s_nop 0
	v_pk_fma_f32 v[50:51], v[38:39], v[12:13], v[50:51]
	s_nop 0
	v_pk_fma_f32 v[50:51], v[48:49], v[8:9], v[50:51]
	s_nop 0
	v_pk_fma_f32 v[42:43], v[42:43], v[4:5], v[50:51]
	s_nop 0
	v_mul_f32_e32 v34, 0xbfb8aa3b, v42
	v_exp_f32_e32 v34, v34
	s_nop 0
	v_add_f32_e32 v34, 1.0, v34
	v_rcp_f32_e32 v50, v34
	v_mul_f32_e32 v34, 0xbfb8aa3b, v43
	v_exp_f32_e32 v34, v34
	s_nop 0
	v_add_f32_e32 v34, 1.0, v34
	v_rcp_f32_e32 v51, v34
	s_nop 0
	v_pk_mul_f32 v[42:43], v[42:43], v[50:51]
	s_nop 0
	v_cvt_pk_bf16_f32 v50, v42, v43
	v_lshlrev_b32_e32 v42, 16, v35
	v_and_b32_e32 v43, 0xffff0000, v35
	v_pk_fma_f32 v[34:35], v[42:43], v[18:19], v[22:23]
	s_nop 0
	v_pk_fma_f32 v[34:35], v[36:37], v[14:15], v[34:35]
	s_nop 0
	v_pk_fma_f32 v[34:35], v[44:45], v[10:11], v[34:35]
	s_nop 0
	v_pk_fma_f32 v[34:35], v[40:41], v[6:7], v[34:35]
	s_nop 0
	v_mul_f32_e32 v40, 0xbfb8aa3b, v34
	v_mul_f32_e32 v41, 0xbfb8aa3b, v35
	v_exp_f32_e32 v40, v40
	v_exp_f32_e32 v41, v41
	v_add_f32_e32 v40, 1.0, v40
	v_add_f32_e32 v41, 1.0, v41
	v_rcp_f32_e32 v40, v40
	v_rcp_f32_e32 v41, v41
	s_nop 0
	v_pk_mul_f32 v[34:35], v[34:35], v[40:41]
	s_nop 0
	v_cvt_pk_bf16_f32 v51, v34, v35
	s_waitcnt vmcnt(4)
	v_lshlrev_b32_e32 v34, 16, v32
	v_and_b32_e32 v35, 0xffff0000, v32
	v_pk_fma_f32 v[40:41], v[34:35], v[16:17], v[20:21]
	s_nop 0
	v_pk_fma_f32 v[40:41], v[46:47], v[12:13], v[40:41]
	s_nop 0
	v_pk_fma_f32 v[40:41], v[38:39], v[8:9], v[40:41]
	s_nop 0
	v_pk_fma_f32 v[40:41], v[48:49], v[4:5], v[40:41]
	s_nop 0
	v_mul_f32_e32 v32, 0xbfb8aa3b, v40
	v_exp_f32_e32 v32, v32
	s_nop 0
	v_add_f32_e32 v32, 1.0, v32
	v_rcp_f32_e32 v48, v32
	v_mul_f32_e32 v32, 0xbfb8aa3b, v41
	v_exp_f32_e32 v32, v32
	s_nop 0
	v_add_f32_e32 v32, 1.0, v32
	v_rcp_f32_e32 v49, v32
	v_lshlrev_b32_e32 v32, 16, v33
	v_and_b32_e32 v33, 0xffff0000, v33
	v_pk_mul_f32 v[40:41], v[40:41], v[48:49]
	v_pk_fma_f32 v[48:49], v[32:33], v[18:19], v[22:23]
	v_cvt_pk_bf16_f32 v40, v40, v41
	v_pk_fma_f32 v[48:49], v[42:43], v[14:15], v[48:49]
	s_nop 0
	v_pk_fma_f32 v[48:49], v[36:37], v[10:11], v[48:49]
	s_nop 0
	v_pk_fma_f32 v[44:45], v[44:45], v[6:7], v[48:49]
	s_nop 0
	v_mul_f32_e32 v41, 0xbfb8aa3b, v44
	v_exp_f32_e32 v41, v41
	s_nop 0
	v_add_f32_e32 v41, 1.0, v41
	v_rcp_f32_e32 v48, v41
	v_mul_f32_e32 v41, 0xbfb8aa3b, v45
	v_exp_f32_e32 v41, v41
	s_nop 0
	v_add_f32_e32 v41, 1.0, v41
	v_rcp_f32_e32 v49, v41
	s_nop 0
	v_pk_mul_f32 v[44:45], v[44:45], v[48:49]
	s_nop 0
	v_cvt_pk_bf16_f32 v41, v44, v45
	ds_write2_b64 v2, v[50:51], v[40:41] offset0:84 offset1:118
	s_waitcnt vmcnt(3)
	v_lshlrev_b32_e32 v40, 16, v30
	v_and_b32_e32 v41, 0xffff0000, v30
	v_pk_fma_f32 v[44:45], v[40:41], v[16:17], v[20:21]
	s_nop 0
	v_pk_fma_f32 v[44:45], v[34:35], v[12:13], v[44:45]
	s_nop 0
	v_pk_fma_f32 v[44:45], v[46:47], v[8:9], v[44:45]
	s_nop 0
	v_pk_fma_f32 v[38:39], v[38:39], v[4:5], v[44:45]
	s_nop 0
	v_mul_f32_e32 v30, 0xbfb8aa3b, v38
	v_exp_f32_e32 v30, v30
	s_nop 0
	v_add_f32_e32 v30, 1.0, v30
	v_rcp_f32_e32 v44, v30
	v_mul_f32_e32 v30, 0xbfb8aa3b, v39
	v_exp_f32_e32 v30, v30
	s_nop 0
	v_add_f32_e32 v30, 1.0, v30
	v_rcp_f32_e32 v45, v30
	v_lshlrev_b32_e32 v30, 16, v31
	v_and_b32_e32 v31, 0xffff0000, v31
	v_pk_mul_f32 v[38:39], v[38:39], v[44:45]
	v_pk_fma_f32 v[44:45], v[30:31], v[18:19], v[22:23]
	v_cvt_pk_bf16_f32 v38, v38, v39
	v_pk_fma_f32 v[44:45], v[32:33], v[14:15], v[44:45]
	s_nop 0
	v_pk_fma_f32 v[44:45], v[42:43], v[10:11], v[44:45]
	s_nop 0
	v_pk_fma_f32 v[36:37], v[36:37], v[6:7], v[44:45]
	s_nop 0
	v_mul_f32_e32 v39, 0xbfb8aa3b, v36
	v_exp_f32_e32 v39, v39
	s_nop 0
	v_add_f32_e32 v39, 1.0, v39
	v_rcp_f32_e32 v44, v39
	v_mul_f32_e32 v39, 0xbfb8aa3b, v37
	v_exp_f32_e32 v39, v39
	s_nop 0
	v_add_f32_e32 v39, 1.0, v39
	v_rcp_f32_e32 v45, v39
	s_nop 0
	v_pk_mul_f32 v[36:37], v[36:37], v[44:45]
	s_nop 0
	v_cvt_pk_bf16_f32 v39, v36, v37
	s_waitcnt vmcnt(2)
	v_lshlrev_b32_e32 v36, 16, v28
	v_and_b32_e32 v37, 0xffff0000, v28
	v_pk_fma_f32 v[44:45], v[36:37], v[16:17], v[20:21]
	s_nop 0
	v_pk_fma_f32 v[44:45], v[40:41], v[12:13], v[44:45]
	s_nop 0
	v_pk_fma_f32 v[44:45], v[34:35], v[8:9], v[44:45]
	s_nop 0
	v_pk_fma_f32 v[44:45], v[46:47], v[4:5], v[44:45]
	s_nop 0
	v_mul_f32_e32 v28, 0xbfb8aa3b, v44
	v_exp_f32_e32 v28, v28
	s_nop 0
	v_add_f32_e32 v28, 1.0, v28
	v_rcp_f32_e32 v46, v28
	v_mul_f32_e32 v28, 0xbfb8aa3b, v45
	v_exp_f32_e32 v28, v28
	s_nop 0
	v_add_f32_e32 v28, 1.0, v28
	v_rcp_f32_e32 v47, v28
	s_nop 0
	v_pk_mul_f32 v[44:45], v[44:45], v[46:47]
	s_nop 0
	v_cvt_pk_bf16_f32 v28, v44, v45
	v_lshlrev_b32_e32 v44, 16, v29
	v_and_b32_e32 v45, 0xffff0000, v29
	v_pk_fma_f32 v[46:47], v[44:45], v[18:19], v[22:23]
	s_nop 0
	v_pk_fma_f32 v[46:47], v[30:31], v[14:15], v[46:47]
	s_nop 0
	v_pk_fma_f32 v[46:47], v[32:33], v[10:11], v[46:47]
	s_nop 0
	v_pk_fma_f32 v[42:43], v[42:43], v[6:7], v[46:47]
	s_nop 0
	v_mul_f32_e32 v29, 0xbfb8aa3b, v42
	v_exp_f32_e32 v29, v29
	s_nop 0
	v_add_f32_e32 v29, 1.0, v29
	v_rcp_f32_e32 v46, v29
	v_mul_f32_e32 v29, 0xbfb8aa3b, v43
	v_exp_f32_e32 v29, v29
	s_nop 0
	v_add_f32_e32 v29, 1.0, v29
	v_rcp_f32_e32 v47, v29
	s_nop 0
	v_pk_mul_f32 v[42:43], v[42:43], v[46:47]
	s_nop 0
	v_cvt_pk_bf16_f32 v29, v42, v43
	ds_write2_b64 v2, v[38:39], v[28:29] offset0:152 offset1:186
	s_waitcnt vmcnt(1)
	v_lshlrev_b32_e32 v28, 16, v26
	v_and_b32_e32 v29, 0xffff0000, v26
	v_pk_fma_f32 v[38:39], v[28:29], v[16:17], v[20:21]
	s_nop 0
	v_pk_fma_f32 v[38:39], v[36:37], v[12:13], v[38:39]
	s_nop 0
	v_pk_fma_f32 v[38:39], v[40:41], v[8:9], v[38:39]
	s_nop 0
	v_pk_fma_f32 v[34:35], v[34:35], v[4:5], v[38:39]
	s_nop 0
	v_mul_f32_e32 v26, 0xbfb8aa3b, v34
	v_exp_f32_e32 v26, v26
	s_nop 0
	v_add_f32_e32 v26, 1.0, v26
	v_rcp_f32_e32 v38, v26
	v_mul_f32_e32 v26, 0xbfb8aa3b, v35
	v_exp_f32_e32 v26, v26
	s_nop 0
	v_add_f32_e32 v26, 1.0, v26
	v_rcp_f32_e32 v39, v26
	s_nop 0
	v_pk_mul_f32 v[34:35], v[34:35], v[38:39]
	s_nop 0
	v_cvt_pk_bf16_f32 v26, v34, v35
	v_lshlrev_b32_e32 v34, 16, v27
	v_and_b32_e32 v35, 0xffff0000, v27
	v_pk_fma_f32 v[38:39], v[34:35], v[18:19], v[22:23]
	s_nop 0
	v_pk_fma_f32 v[38:39], v[44:45], v[14:15], v[38:39]
	s_nop 0
	v_pk_fma_f32 v[38:39], v[30:31], v[10:11], v[38:39]
	s_nop 0
	v_pk_fma_f32 v[32:33], v[32:33], v[6:7], v[38:39]
	s_nop 0
	v_mul_f32_e32 v27, 0xbfb8aa3b, v32
	v_exp_f32_e32 v27, v27
	s_nop 0
	v_add_f32_e32 v27, 1.0, v27
	v_rcp_f32_e32 v38, v27
	v_mul_f32_e32 v27, 0xbfb8aa3b, v33
	v_exp_f32_e32 v27, v27
	s_nop 0
	v_add_f32_e32 v27, 1.0, v27
	v_rcp_f32_e32 v39, v27
	s_nop 0
	v_pk_mul_f32 v[32:33], v[32:33], v[38:39]
	s_nop 0
	v_cvt_pk_bf16_f32 v27, v32, v33
	s_waitcnt vmcnt(0)
	v_lshlrev_b32_e32 v32, 16, v24
	v_and_b32_e32 v33, 0xffff0000, v24
	v_pk_fma_f32 v[16:17], v[32:33], v[16:17], v[20:21]
	s_nop 0
	v_pk_fma_f32 v[12:13], v[28:29], v[12:13], v[16:17]
	s_nop 0
	v_pk_fma_f32 v[8:9], v[36:37], v[8:9], v[12:13]
	s_nop 0
	v_pk_fma_f32 v[4:5], v[40:41], v[4:5], v[8:9]
	s_nop 0
	v_mul_f32_e32 v8, 0xbfb8aa3b, v4
	v_mul_f32_e32 v9, 0xbfb8aa3b, v5
	v_exp_f32_e32 v8, v8
	v_exp_f32_e32 v9, v9
	v_add_f32_e32 v8, 1.0, v8
	v_add_f32_e32 v9, 1.0, v9
	v_rcp_f32_e32 v8, v8
	v_rcp_f32_e32 v9, v9
	s_nop 0
	v_pk_mul_f32 v[4:5], v[4:5], v[8:9]
	v_lshlrev_b32_e32 v8, 16, v25
	v_and_b32_e32 v9, 0xffff0000, v25
	v_pk_fma_f32 v[8:9], v[8:9], v[18:19], v[22:23]
	v_cvt_pk_bf16_f32 v4, v4, v5
	v_pk_fma_f32 v[8:9], v[34:35], v[14:15], v[8:9]
	s_nop 0
	v_pk_fma_f32 v[8:9], v[44:45], v[10:11], v[8:9]
	s_nop 0
	v_pk_fma_f32 v[6:7], v[30:31], v[6:7], v[8:9]
	s_nop 0
	v_mul_f32_e32 v5, 0xbfb8aa3b, v6
	v_exp_f32_e32 v5, v5
	s_nop 0
	v_add_f32_e32 v5, 1.0, v5
	v_rcp_f32_e32 v8, v5
	v_mul_f32_e32 v5, 0xbfb8aa3b, v7
	v_exp_f32_e32 v5, v5
	s_nop 0
	v_add_f32_e32 v5, 1.0, v5
	v_rcp_f32_e32 v9, v5
	s_nop 0
	v_pk_mul_f32 v[6:7], v[6:7], v[8:9]
	s_nop 0
	v_cvt_pk_bf16_f32 v5, v6, v7
	ds_write2_b64 v2, v[26:27], v[4:5] offset0:220 offset1:254
	s_waitcnt lgkmcnt(0)
	s_barrier
	s_cbranch_vccnz .LBB0_565

.LBB0_587:
	v_mov_b32_e32 v30, 0
	v_mov_b32_e32 v31, 0
	v_mov_b32_e32 v62, 0
	v_mov_b32_e32 v28, 0
	v_mov_b32_e32 v29, 0
	v_mov_b32_e32 v63, v62
	v_mov_b32_e32 v66, v62
	v_mov_b32_e32 v67, v62
	s_and_b64 vcc, exec, s[50:51]
	v_mov_b32_e32 v59, 0
	s_cbranch_vccz .LBB0_560
	s_branch .LBB0_561
